# P1 SW mainloop: double-buffered MFMA fragments, slice k+2 LDS-DMA issued mid-iteration after an early buffer-release barrier (two slices in flight)
# speedup vs baseline: 1.0021x; 1.0021x over previous
; template <bool SW>
; __device__ __forceinline__ void gemm_mainloop(const bf16_t* __restrict__ A, int lda, const bf16_t* __restrict__ Bt, int ldb, int K,
;                                               f32x16 (&acc)[2][2], char* lds, int kstart) {
;   const int tid = threadIdx.x, lane = tid & 63, wid = tid >> 6;
;   const int wr = wid >> 1, wc = wid & 1, l31 = lane & 31, hh = lane >> 5;
;   const int lrow = wid * 32 + (lane >> 3);
;   const int nk = K >> 6;
;   kstart &= (nk - 1);
;   const bf16_t* ap[4]; const bf16_t* bp[4];
; #pragma unroll
;   for (int i = 0; i < 4; ++i) {
;     const int row = lrow + 8 * i; const int ch = (lane & 7) ^ ((row >> 1) & 7);
;     ap[i] = A + (size_t)row * lda + ch * 8; bp[i] = Bt + (size_t)row * ldb + ch * 8;
;   }
;   char* ldst = lds + (wid * 32) * 128 + lane * 16;
; #pragma unroll
;   for (int i = 0; i < 4; ++i) { glds16(ap[i] + kstart * 64, ldst + i * 1024); glds16(bp[i] + kstart * 64, ldst + 16384 + i * 1024); }
;   asm volatile("s_waitcnt vmcnt(0)" ::: "memory");
;   __syncthreads();
;   const int swz = (l31 >> 1) & 7;
;   const int roffA = (wr * 64 + l31) * 128, roffB = 16384 + (wc * 64 + l31) * 128;
; #pragma unroll 1
;   for (int kt = 0; kt < nk; ++kt) {
;     const bool more = (kt + 1 < nk);
;     if (more) {
;       char* d = ldst + ((kt + 1) & 1) * GEMM_BUF;
;       const int ko = ((kt + 1 + kstart) & (nk - 1)) * 64;
; #pragma unroll
;       for (int i = 0; i < 4; ++i) { glds16(ap[i] + ko, d + i * 1024); glds16(bp[i] + ko, d + 16384 + i * 1024); }
;     }
;     const char* base = lds + (kt & 1) * GEMM_BUF;
; #pragma unroll
;     for (int ks = 0; ks < 4; ++ks) {
;       const int co = ((2 * ks + hh) ^ swz) * 16;
;       bf16x8 a0 = *(const bf16x8*)(base + roffA + co), a1 = *(const bf16x8*)(base + roffA + 32 * 128 + co);
;       bf16x8 b0 = *(const bf16x8*)(base + roffB + co), b1 = *(const bf16x8*)(base + roffB + 32 * 128 + co);
.LBB0_172:
	s_andn2_b64 vcc, exec, s[0:1]
	s_mov_b32 s34, 2
	s_cbranch_vccnz .LBB0_277
	s_lshl_b32 s53, s52, 7
	s_lshl_b32 s54, s51, 7
	s_cmpk_gt_i32 s52, 0xff
	s_cselect_b64 s[38:39], -1, 0
	s_and_b32 s2, s51, -8
	s_mul_i32 s0, s52, 0x44000
	s_mul_hi_i32 s1, s53, 0x880
	s_add_u32 s0, s33, s0
	s_addc_u32 s1, s27, s1
	s_add_i32 s3, s51, s52
	v_lshl_add_u64 v[0:1], s[0:1], 0, v[64:65]
	v_mov_b32_e32 v109, v65
	s_lshl_b32 s55, s3, 7
	v_lshl_add_u64 v[116:117], v[0:1], 0, v[108:109]
	v_lshl_add_u64 v[0:1], v[66:67], 1, s[0:1]
	v_mov_b32_e32 v111, v65
	s_and_b32 s3, s55, 0x380
	v_lshl_add_u64 v[118:119], v[0:1], 0, v[110:111]
	v_lshl_add_u64 v[0:1], v[68:69], 1, s[0:1]
	s_lshl_b32 s46, s3, 1
	v_lshl_add_u64 v[120:121], v[0:1], 0, v[108:109]
	v_lshl_add_u64 v[0:1], v[70:71], 1, s[0:1]
	s_mov_b32 s47, s77
	v_readfirstlane_b32 s0, v147
	v_lshl_add_u64 v[122:123], v[0:1], 0, v[110:111]
	v_lshl_add_u64 v[0:1], v[116:117], 0, s[46:47]
	s_mov_b32 m0, s0
	s_cmp_lg_u32 s2, 16
	global_load_lds_dwordx4 v[0:1], off
	v_lshl_add_u64 v[128:129], v[118:119], 0, s[46:47]
	v_lshl_add_u64 v[126:127], v[120:121], 0, s[46:47]
	v_lshl_add_u64 v[124:125], v[122:123], 0, s[46:47]
	s_mov_b64 s[0:1], -1
	s_cbranch_scc0 .LBB0_261
	s_mul_i32 s0, s54, 0x880
	s_mul_hi_i32 s1, s54, 0x880
	s_add_u32 s0, s96, s0
	s_addc_u32 s1, s97, s1
	v_lshl_add_u64 v[0:1], s[0:1], 0, v[64:65]
	v_lshl_add_u64 v[130:131], v[0:1], 0, v[108:109]
	v_lshl_add_u64 v[0:1], v[66:67], 1, s[0:1]
	v_lshl_add_u64 v[132:133], v[0:1], 0, v[110:111]
	v_lshl_add_u64 v[0:1], v[68:69], 1, s[0:1]
	v_lshl_add_u64 v[134:135], v[0:1], 0, v[108:109]
	v_lshl_add_u64 v[0:1], v[70:71], 1, s[0:1]
	v_readfirstlane_b32 s0, v156
	v_lshl_add_u64 v[136:137], v[0:1], 0, v[110:111]
	v_lshl_add_u64 v[0:1], v[130:131], 0, s[46:47]
	s_mov_b32 m0, s0
	v_readfirstlane_b32 s0, v157
	global_load_lds_dwordx4 v[0:1], off
	s_mov_b32 m0, s0
	v_readfirstlane_b32 s0, v158
	global_load_lds_dwordx4 v[128:129], off
	v_lshl_add_u64 v[0:1], v[132:133], 0, s[46:47]
	s_mov_b32 m0, s0
	v_readfirstlane_b32 s0, v159
	global_load_lds_dwordx4 v[0:1], off
	s_mov_b32 m0, s0
	v_readfirstlane_b32 s0, v160
	global_load_lds_dwordx4 v[126:127], off
	v_lshl_add_u64 v[0:1], v[134:135], 0, s[46:47]
	s_mov_b32 m0, s0
	v_readfirstlane_b32 s0, v161
	global_load_lds_dwordx4 v[0:1], off
	s_mov_b32 m0, s0
	v_readfirstlane_b32 s0, v162
	global_load_lds_dwordx4 v[124:125], off
	v_lshl_add_u64 v[0:1], v[136:137], 0, s[46:47]
	s_mov_b32 m0, s0
	s_add_i32 s2, s55, 64
	global_load_lds_dwordx4 v[0:1], off
	v_mov_b32_e32 v0, 0
	s_mov_b32 s34, 0
	s_mov_b32 s3, 0
	v_mov_b32_e32 v1, v0
	v_mov_b32_e32 v2, v0
	v_mov_b32_e32 v3, v0
	v_mov_b32_e32 v4, v0
	v_mov_b32_e32 v5, v0
	v_mov_b32_e32 v6, v0
	v_mov_b32_e32 v7, v0
	v_mov_b32_e32 v8, v0
	v_mov_b32_e32 v9, v0
	v_mov_b32_e32 v10, v0
	v_mov_b32_e32 v11, v0
	v_mov_b32_e32 v12, v0
	v_mov_b32_e32 v13, v0
	v_mov_b32_e32 v14, v0
	v_mov_b32_e32 v15, v0
	v_mov_b32_e32 v16, v0
	v_mov_b32_e32 v17, v0
	v_mov_b32_e32 v18, v0
	v_mov_b32_e32 v19, v0
	v_mov_b32_e32 v20, v0
	v_mov_b32_e32 v21, v0
	v_mov_b32_e32 v22, v0
	v_mov_b32_e32 v23, v0
	v_mov_b32_e32 v24, v0
	v_mov_b32_e32 v25, v0
	v_mov_b32_e32 v26, v0
	v_mov_b32_e32 v27, v0
	v_mov_b32_e32 v28, v0
	v_mov_b32_e32 v29, v0
	v_mov_b32_e32 v30, v0
	v_mov_b32_e32 v31, v0
	v_mov_b32_e32 v32, v0
	v_mov_b32_e32 v33, v0
	v_mov_b32_e32 v34, v0
	v_mov_b32_e32 v35, v0
	v_mov_b32_e32 v36, v0
	v_mov_b32_e32 v37, v0
	v_mov_b32_e32 v38, v0
	v_mov_b32_e32 v39, v0
	v_mov_b32_e32 v40, v0
	v_mov_b32_e32 v41, v0
	v_mov_b32_e32 v42, v0
	v_mov_b32_e32 v43, v0
	v_mov_b32_e32 v44, v0
	v_mov_b32_e32 v45, v0
	v_mov_b32_e32 v46, v0
	v_mov_b32_e32 v47, v0
	v_mov_b32_e32 v48, v0
	v_mov_b32_e32 v49, v0
	v_mov_b32_e32 v50, v0
	v_mov_b32_e32 v51, v0
	v_mov_b32_e32 v52, v0
	v_mov_b32_e32 v53, v0
	v_mov_b32_e32 v54, v0
	v_mov_b32_e32 v55, v0
	v_mov_b32_e32 v56, v0
	v_mov_b32_e32 v57, v0
	v_mov_b32_e32 v58, v0
	v_mov_b32_e32 v59, v0
	v_mov_b32_e32 v60, v0
	v_mov_b32_e32 v61, v0
	v_mov_b32_e32 v62, v0
	v_mov_b32_e32 v63, v0
	s_waitcnt lgkmcnt(0)
	s_barrier
	s_mov_b32 s0, 0x8000
	v_add_u32_e32 v109, s0, v147
	s_and_b32 s0, s2, 0x3c0
	v_add_u32_e32 v111, 0x4000, v109
	s_lshl_b32 s76, s0, 1
	v_readfirstlane_b32 s0, v109
	v_lshl_add_u64 v[210:211], v[116:117], 0, s[76:77]
	s_mov_b32 m0, s0
	v_readfirstlane_b32 s0, v111
	v_add_u32_e32 v111, 0x400, v109
	global_load_lds_dwordx4 v[210:211], off
	v_lshl_add_u64 v[210:211], v[130:131], 0, s[76:77]
	s_mov_b32 m0, s0
	v_readfirstlane_b32 s0, v111
	v_add_u32_e32 v111, 0x4400, v109
	global_load_lds_dwordx4 v[210:211], off
	v_lshl_add_u64 v[210:211], v[118:119], 0, s[76:77]
	s_mov_b32 m0, s0
	v_readfirstlane_b32 s0, v111
	v_add_u32_e32 v111, 0x800, v109
	global_load_lds_dwordx4 v[210:211], off
	v_lshl_add_u64 v[210:211], v[132:133], 0, s[76:77]
	s_mov_b32 m0, s0
	v_readfirstlane_b32 s0, v111
	v_add_u32_e32 v111, 0x4800, v109
	global_load_lds_dwordx4 v[210:211], off
	v_lshl_add_u64 v[210:211], v[120:121], 0, s[76:77]
	s_mov_b32 m0, s0
	v_readfirstlane_b32 s0, v111
	v_add_u32_e32 v111, 0xc00, v109
	global_load_lds_dwordx4 v[210:211], off
	v_lshl_add_u64 v[210:211], v[134:135], 0, s[76:77]
	s_mov_b32 m0, s0
	v_readfirstlane_b32 s0, v111
	v_add_u32_e32 v109, 0x4c00, v109
	global_load_lds_dwordx4 v[210:211], off
	v_lshl_add_u64 v[210:211], v[122:123], 0, s[76:77]
	s_mov_b32 m0, s0
	v_readfirstlane_b32 s0, v109
	global_load_lds_dwordx4 v[210:211], off
	v_lshl_add_u64 v[210:211], v[136:137], 0, s[76:77]
	s_mov_b32 m0, s0
	s_nop 0
	global_load_lds_dwordx4 v[210:211], off
	s_add_i32 s2, s2, 64
	s_waitcnt vmcnt(8)
	s_barrier
	v_add_u32_e32 v111, v150, v151
	v_add_u32_e32 v115, v149, v151
	ds_read_b128 v[138:141], v111 offset:16384
	ds_read_b128 v[168:171], v111 offset:20480
	ds_read_b128 v[164:167], v115
	ds_read_b128 v[190:193], v115 offset:4096
; __device__ __forceinline__ f32x16 mfma32(bf16x8 a, bf16x8 b, f32x16 c) { return __builtin_amdgcn_mfma_f32_32x32x16_bf16(a, b, c, 0, 0, 0); }
; template <bool SW>
; __device__ __forceinline__ void gemm_mainloop(const bf16_t* __restrict__ A, int lda, const bf16_t* __restrict__ Bt, int ldb, int K,
;                                               f32x16 (&acc)[2][2], char* lds, int kstart) {
;     ...
;   for (int kt = 0; kt < nk; ++kt) {
;     const bool more = (kt + 1 < nk);
;     if (more) {
;       char* d = ldst + ((kt + 1) & 1) * GEMM_BUF;
;       const int ko = ((kt + 1 + kstart) & (nk - 1)) * 64;
; #pragma unroll
;       for (int i = 0; i < 4; ++i) { glds16(ap[i] + ko, d + i * 1024); glds16(bp[i] + ko, d + 16384 + i * 1024); }
;     }
;     const char* base = lds + (kt & 1) * GEMM_BUF;
; #pragma unroll
;     for (int ks = 0; ks < 4; ++ks) {
;       const int co = ((2 * ks + hh) ^ swz) * 16;
;       bf16x8 a0 = *(const bf16x8*)(base + roffA + co), a1 = *(const bf16x8*)(base + roffA + 32 * 128 + co);
;       bf16x8 b0 = *(const bf16x8*)(base + roffB + co), b1 = *(const bf16x8*)(base + roffB + 32 * 128 + co);
;       if (SW) {
;         acc[0][0] = mfma32(b0, a0, acc[0][0]); acc[0][1] = mfma32(b1, a0, acc[0][1]);
;         acc[1][0] = mfma32(b0, a1, acc[1][0]); acc[1][1] = mfma32(b1, a1, acc[1][1]);
;       } else {
;         acc[0][0] = mfma32(a0, b0, acc[0][0]); acc[0][1] = mfma32(a0, b1, acc[0][1]);
;         acc[1][0] = mfma32(a1, b0, acc[1][0]); acc[1][1] = mfma32(a1, b1, acc[1][1]);
;       }
;     }
;     asm volatile("s_waitcnt vmcnt(0)" ::: "memory");
;     __syncthreads();
.Lp1_ml_top:
	s_and_b32 s0, s34, 0x8000
	v_or_b32_e32 v109, s0, v150
	v_add_u32_e32 v113, s0, v149
	v_add_u32_e32 v111, v109, v152
	v_add_u32_e32 v115, v113, v152
	ds_read_b128 v[194:197], v111 offset:16384
	ds_read_b128 v[198:201], v111 offset:20480
	ds_read_b128 v[202:205], v115
	ds_read_b128 v[206:209], v115 offset:4096
	s_waitcnt lgkmcnt(4)
	v_mfma_f32_32x32x16_bf16 v[48:63], v[138:141], v[164:167], v[48:63]
	v_mfma_f32_32x32x16_bf16 v[32:47], v[168:171], v[164:167], v[32:47]
	v_mfma_f32_32x32x16_bf16 v[16:31], v[138:141], v[190:193], v[16:31]
	v_mfma_f32_32x32x16_bf16 v[0:15], v[168:171], v[190:193], v[0:15]
	v_add_u32_e32 v111, v109, v153
	v_add_u32_e32 v115, v113, v153
	ds_read_b128 v[138:141], v111 offset:16384
	ds_read_b128 v[168:171], v111 offset:20480
	ds_read_b128 v[164:167], v115
	ds_read_b128 v[190:193], v115 offset:4096
	s_waitcnt lgkmcnt(4)
	v_mfma_f32_32x32x16_bf16 v[48:63], v[194:197], v[202:205], v[48:63]
	v_mfma_f32_32x32x16_bf16 v[32:47], v[198:201], v[202:205], v[32:47]
	v_mfma_f32_32x32x16_bf16 v[16:31], v[194:197], v[206:209], v[16:31]
	v_mfma_f32_32x32x16_bf16 v[0:15], v[198:201], v[206:209], v[0:15]
	v_add_u32_e32 v111, v109, v154
	v_add_u32_e32 v115, v113, v154
	ds_read_b128 v[194:197], v111 offset:16384
	ds_read_b128 v[198:201], v111 offset:20480
	ds_read_b128 v[202:205], v115
	ds_read_b128 v[206:209], v115 offset:4096
	s_waitcnt lgkmcnt(4)
	v_mfma_f32_32x32x16_bf16 v[48:63], v[138:141], v[164:167], v[48:63]
	v_mfma_f32_32x32x16_bf16 v[32:47], v[168:171], v[164:167], v[32:47]
	s_waitcnt lgkmcnt(0)
	s_barrier
	s_cmp_lt_u32 s3, 14
	s_cbranch_scc0 .Lp1_ml_nodma
	s_and_b32 s0, s34, 0x8000
	v_add_u32_e32 v109, s0, v147
	s_and_b32 s0, s2, 0x3c0
	v_add_u32_e32 v111, 0x4000, v109
	s_lshl_b32 s76, s0, 1
	v_readfirstlane_b32 s0, v109
	v_lshl_add_u64 v[210:211], v[116:117], 0, s[76:77]
	s_mov_b32 m0, s0
	v_readfirstlane_b32 s0, v111
	v_add_u32_e32 v111, 0x400, v109
	global_load_lds_dwordx4 v[210:211], off
	v_lshl_add_u64 v[210:211], v[130:131], 0, s[76:77]
	s_mov_b32 m0, s0
	v_readfirstlane_b32 s0, v111
	v_add_u32_e32 v111, 0x4400, v109
	global_load_lds_dwordx4 v[210:211], off
	v_lshl_add_u64 v[210:211], v[118:119], 0, s[76:77]
	s_mov_b32 m0, s0
	v_readfirstlane_b32 s0, v111
	v_add_u32_e32 v111, 0x800, v109
	global_load_lds_dwordx4 v[210:211], off
	v_lshl_add_u64 v[210:211], v[132:133], 0, s[76:77]
	s_mov_b32 m0, s0
	v_readfirstlane_b32 s0, v111
	v_add_u32_e32 v111, 0x4800, v109
	global_load_lds_dwordx4 v[210:211], off
	v_lshl_add_u64 v[210:211], v[120:121], 0, s[76:77]
	s_mov_b32 m0, s0
	v_readfirstlane_b32 s0, v111
	v_add_u32_e32 v111, 0xc00, v109
	global_load_lds_dwordx4 v[210:211], off
	v_lshl_add_u64 v[210:211], v[134:135], 0, s[76:77]
	s_mov_b32 m0, s0
	v_readfirstlane_b32 s0, v111
	v_add_u32_e32 v109, 0x4c00, v109
	global_load_lds_dwordx4 v[210:211], off
	v_lshl_add_u64 v[210:211], v[122:123], 0, s[76:77]
	s_mov_b32 m0, s0
	v_readfirstlane_b32 s0, v109
	global_load_lds_dwordx4 v[210:211], off
	v_lshl_add_u64 v[210:211], v[136:137], 0, s[76:77]
	s_mov_b32 m0, s0
	s_nop 0
	global_load_lds_dwordx4 v[210:211], off
.Lp1_ml_nodma:
	v_mfma_f32_32x32x16_bf16 v[16:31], v[138:141], v[190:193], v[16:31]
	v_mfma_f32_32x32x16_bf16 v[0:15], v[168:171], v[190:193], v[0:15]
	s_cmp_lt_u32 s3, 14
	s_cbranch_scc0 .Lp1_ml_w0
	s_waitcnt vmcnt(8)
	s_branch .Lp1_ml_wd

; __device__ __forceinline__ f32x16 mfma32(bf16x8 a, bf16x8 b, f32x16 c) { return __builtin_amdgcn_mfma_f32_32x32x16_bf16(a, b, c, 0, 0, 0); }
; template <bool SW>
; __device__ __forceinline__ void gemm_mainloop(const bf16_t* __restrict__ A, int lda, const bf16_t* __restrict__ Bt, int ldb, int K,
;                                               f32x16 (&acc)[2][2], char* lds, int kstart) {
;     ...
;   for (int kt = 0; kt < nk; ++kt) {
;     const bool more = (kt + 1 < nk);
;     if (more) {
;       char* d = ldst + ((kt + 1) & 1) * GEMM_BUF;
;       const int ko = ((kt + 1 + kstart) & (nk - 1)) * 64;
; #pragma unroll
;       for (int i = 0; i < 4; ++i) { glds16(ap[i] + ko, d + i * 1024); glds16(bp[i] + ko, d + 16384 + i * 1024); }
;     }
;     const char* base = lds + (kt & 1) * GEMM_BUF;
; #pragma unroll
;     for (int ks = 0; ks < 4; ++ks) {
;       const int co = ((2 * ks + hh) ^ swz) * 16;
;       bf16x8 a0 = *(const bf16x8*)(base + roffA + co), a1 = *(const bf16x8*)(base + roffA + 32 * 128 + co);
;       bf16x8 b0 = *(const bf16x8*)(base + roffB + co), b1 = *(const bf16x8*)(base + roffB + 32 * 128 + co);
;       if (SW) {
;         acc[0][0] = mfma32(b0, a0, acc[0][0]); acc[0][1] = mfma32(b1, a0, acc[0][1]);
;         acc[1][0] = mfma32(b0, a1, acc[1][0]); acc[1][1] = mfma32(b1, a1, acc[1][1]);
;       } else {
;         acc[0][0] = mfma32(a0, b0, acc[0][0]); acc[0][1] = mfma32(a0, b1, acc[0][1]);
;         acc[1][0] = mfma32(a1, b0, acc[1][0]); acc[1][1] = mfma32(a1, b1, acc[1][1]);
;       }
;     }
;     asm volatile("s_waitcnt vmcnt(0)" ::: "memory");
;     __syncthreads();
.Lp1_ml_wd:
	s_barrier
	s_add_i32 s3, s3, 1
	s_add_i32 s2, s2, 64
	s_add_i32 s34, s34, 0x8000
	s_cmp_lg_u32 s3, 16
	s_cbranch_scc0 .Lp1_ml_last
	s_and_b32 s0, s34, 0x8000
	v_or_b32_e32 v109, s0, v150
	v_add_u32_e32 v113, s0, v149
	v_add_u32_e32 v111, v109, v151
	v_add_u32_e32 v115, v113, v151
	ds_read_b128 v[138:141], v111 offset:16384
	ds_read_b128 v[168:171], v111 offset:20480
	ds_read_b128 v[164:167], v115
	ds_read_b128 v[190:193], v115 offset:4096
.Lp1_ml_last:
	v_mfma_f32_32x32x16_bf16 v[48:63], v[194:197], v[202:205], v[48:63]
	v_mfma_f32_32x32x16_bf16 v[32:47], v[198:201], v[202:205], v[32:47]
	v_mfma_f32_32x32x16_bf16 v[16:31], v[194:197], v[206:209], v[16:31]
	v_mfma_f32_32x32x16_bf16 v[0:15], v[198:201], v[206:209], v[0:15]
	s_cmp_lg_u32 s3, 16
	s_cbranch_scc1 .Lp1_ml_top
